# RESID epilogue: next row-group loads issued before the row-sum atomic so in-order vmcnt retirement does not wait on the atomic; waits recounted
# baseline (speedup 1.0000x reference)
; template <int EPI>
; __device__ __forceinline__ void gemm_epilogue(const f32x4 (&acc)[2][2][4][2], const Unit& u, int wr, int wc, int fr, int fq,
;                                               const EpiArgs& ea, const float (&rs_pre)[2][4]) {
;     ...
;     EPI_LOAD_ROW(0, hc, lc, pc);
; #pragma unroll
;     for (int it = 0; it < 8; ++it) {
;       const int ai = it >> 2, m = it & 3;
;       if (it + 1 < 8) EPI_LOAD_ROW(it + 1, hn, ln_, pq);
;       const int row = row0 + ai * 128 + m * 16;
;       float sq = 0.f;
; #pragma unroll
;       for (int bj = 0; bj < 2; ++bj) {
;         const size_t idx = (size_t)row * 1024 + lcp + bj * 32;
;         const uint32_t hw[4] = {hc[bj].x, hc[bj].y, hc[bj].z, hc[bj].w};
;         const uint32_t lw[4] = {lc[bj].x, lc[bj].y, lc[bj].z, lc[bj].w};
;         const uint32_t pw[4] = {pc[bj].x, pc[bj].y, pc[bj].z, pc[bj].w};
;         uint32_t ho[4], lo_[4];
; #pragma unroll
;         for (int n = 0; n < 2; ++n) {
;           f32x4 xv;
;           xv[0] = __uint_as_float(hw[2 * n] << 16) + __uint_as_float(lw[2 * n] << 16);
;           xv[1] = __uint_as_float(hw[2 * n] & 0xffff0000u) + __uint_as_float(lw[2 * n] & 0xffff0000u);
;           xv[2] = __uint_as_float(hw[2 * n + 1] << 16) + __uint_as_float(lw[2 * n + 1] << 16);
;           xv[3] = __uint_as_float(hw[2 * n + 1] & 0xffff0000u) + __uint_as_float(lw[2 * n + 1] & 0xffff0000u);
;           const f32x4 a = acc[ai][bj][m][n];
;           f32x4 v;
;           if constexpr (EPI == EPI_PLEGATE) {
;             const float rs = rsr[ai][m], rpe = rper[ai][m];
;             const float pv[4] = {__uint_as_float(pw[2 * n] << 16), __uint_as_float(pw[2 * n] & 0xffff0000u),
;                                  __uint_as_float(pw[2 * n + 1] << 16), __uint_as_float(pw[2 * n + 1] & 0xffff0000u)};
; #pragma unroll
;             for (int i = 0; i < 4; ++i) v[i] = xv[i] + sigmoidf_(a[i] * rs) * (pv[i] * rpe);
;           } else {
;             v = xv + a * ea.alpha;
;           }
;           const uint2 hnew = pack4(v);
;           ho[2 * n] = hnew.x; ho[2 * n + 1] = hnew.y;
;           if (ea.xf32_out) {
;             *reinterpret_cast<f32x4*>(ea.xf32_out + idx + 4 * n) = v;
;           } else {
;             f32x4 r;
;             r[0] = v[0] - __uint_as_float(hnew.x << 16);
;             r[1] = v[1] - __uint_as_float(hnew.x & 0xffff0000u);
.LBB0_869:
	v_lshl_add_u32 v168, s96, 8, v174
	v_lshl_add_u32 v166, s66, 8, v176
	v_ashrrev_i32_e32 v169, 31, v168
	v_lshlrev_b64 v[130:131], 10, v[168:169]
	v_ashrrev_i32_e32 v167, 31, v166
	v_lshl_add_u64 v[130:131], v[130:131], 0, v[166:167]
	v_lshlrev_b64 v[172:173], 1, v[130:131]
	v_lshl_add_u64 v[130:131], s[68:69], 0, v[172:173]
	v_lshl_add_u64 v[132:133], s[88:89], 0, v[172:173]
	global_load_dwordx4 v[154:157], v[130:131], off
	global_load_dwordx4 v[178:181], v[132:133], off
	global_load_dwordx4 v[146:149], v[130:131], off offset:64
	global_load_dwordx4 v[150:153], v[132:133], off offset:64
	v_or_b32_e32 v130, 16, v168
	v_ashrrev_i32_e32 v131, 31, v130
	v_lshlrev_b64 v[130:131], 10, v[130:131]
	v_lshl_add_u64 v[130:131], v[130:131], 0, v[166:167]
	v_lshlrev_b64 v[170:171], 1, v[130:131]
	v_lshl_add_u64 v[130:131], s[68:69], 0, v[170:171]
	v_lshl_add_u64 v[134:135], s[88:89], 0, v[170:171]
	global_load_dwordx4 v[138:141], v[130:131], off
	global_load_dwordx4 v[142:145], v[134:135], off
	s_nop 0
	global_load_dwordx4 v[130:133], v[130:131], off offset:64
	s_nop 0
	global_load_dwordx4 v[134:137], v[134:135], off offset:64
	s_waitcnt vmcnt(4)
	v_lshlrev_b32_e32 v186, 16, v154
	v_lshlrev_b32_e32 v188, 16, v178
	v_and_b32_e32 v187, 0xffff0000, v154
	v_and_b32_e32 v189, 0xffff0000, v178
	v_lshlrev_b32_e32 v154, 16, v155
	v_lshlrev_b32_e32 v178, 16, v179
	v_and_b32_e32 v155, 0xffff0000, v155
	v_and_b32_e32 v179, 0xffff0000, v179
	v_pk_add_f32 v[186:187], v[186:187], v[188:189]
	v_pk_add_f32 v[154:155], v[154:155], v[178:179]
	v_pk_fma_f32 v[178:179], s[6:7], v[126:127], v[186:187]
	v_pk_fma_f32 v[128:129], s[60:61], v[128:129], v[154:155]
	v_cvt_pk_bf16_f32 v154, v178, v179
	s_nop 0
	v_cvt_pk_bf16_f32 v155, v128, v129
	v_lshlrev_b32_e32 v126, 16, v154
	v_and_b32_e32 v127, 0xffff0000, v154
	v_lshlrev_b32_e32 v182, 16, v155
	v_sub_f32_e32 v126, v178, v126
	v_sub_f32_e32 v127, v179, v127
	v_sub_f32_e32 v182, v128, v182
	v_and_b32_e32 v185, 0xffff0000, v155
	v_sub_f32_e32 v185, v129, v185
	v_cvt_pk_bf16_f32 v126, v126, v127
	v_cvt_pk_bf16_f32 v127, v182, v185
	v_mul_f32_e32 v182, v179, v179
	v_fmac_f32_e32 v182, v178, v178
	v_fmac_f32_e32 v182, v128, v128
	v_fmac_f32_e32 v182, v129, v129
	v_lshlrev_b32_e32 v128, 16, v156
	v_lshlrev_b32_e32 v178, 16, v180
	v_and_b32_e32 v129, 0xffff0000, v156
	v_and_b32_e32 v179, 0xffff0000, v180
	v_lshlrev_b32_e32 v156, 16, v157
	v_lshlrev_b32_e32 v180, 16, v181
	v_and_b32_e32 v157, 0xffff0000, v157
	v_and_b32_e32 v181, 0xffff0000, v181
	v_pk_add_f32 v[128:129], v[128:129], v[178:179]
	v_pk_add_f32 v[156:157], v[156:157], v[180:181]
	v_pk_fma_f32 v[122:123], s[6:7], v[122:123], v[128:129]
	v_pk_fma_f32 v[124:125], s[60:61], v[124:125], v[156:157]
	v_cvt_pk_bf16_f32 v156, v122, v123
	s_nop 0
	v_and_b32_e32 v129, 0xffff0000, v156
	v_sub_f32_e32 v129, v123, v129
	v_mul_f32_e32 v123, v123, v123
	v_fmac_f32_e32 v123, v122, v122
	v_cvt_pk_bf16_f32 v157, v124, v125
	v_lshlrev_b32_e32 v128, 16, v156
	v_lshlrev_b32_e32 v178, 16, v157
	v_fmac_f32_e32 v123, v124, v124
	v_sub_f32_e32 v128, v122, v128
	v_sub_f32_e32 v178, v124, v178
	v_and_b32_e32 v179, 0xffff0000, v157
	v_fmac_f32_e32 v123, v125, v125
	v_sub_f32_e32 v179, v125, v179
	v_cvt_pk_bf16_f32 v128, v128, v129
	v_cvt_pk_bf16_f32 v129, v178, v179
	v_add_f32_e32 v178, v182, v123
	v_lshl_add_u64 v[122:123], s[46:47], 0, v[172:173]
	v_lshl_add_u64 v[124:125], s[70:71], 0, v[172:173]
	global_store_dwordx4 v[122:123], v[154:157], off
	global_store_dwordx4 v[124:125], v[126:129], off
	s_nop 1
	v_lshlrev_b32_e32 v126, 16, v146
	v_lshlrev_b32_e32 v128, 16, v150
	v_and_b32_e32 v127, 0xffff0000, v146
	v_and_b32_e32 v129, 0xffff0000, v150
	v_lshlrev_b32_e32 v146, 16, v147
	v_lshlrev_b32_e32 v150, 16, v151
	v_and_b32_e32 v147, 0xffff0000, v147
	v_and_b32_e32 v151, 0xffff0000, v151
	v_pk_add_f32 v[126:127], v[126:127], v[128:129]
	v_pk_add_f32 v[128:129], v[146:147], v[150:151]
	s_nop 0
	v_pk_fma_f32 v[120:121], s[60:61], v[120:121], v[128:129]
	v_pk_fma_f32 v[128:129], s[6:7], v[118:119], v[126:127]
	v_cvt_pk_bf16_f32 v119, v120, v121
	s_nop 0
	v_cvt_pk_bf16_f32 v118, v128, v129
	v_lshlrev_b32_e32 v146, 16, v119
	v_and_b32_e32 v127, 0xffff0000, v118
	v_sub_f32_e32 v127, v129, v127
	v_mul_f32_e32 v129, v129, v129
	v_fmac_f32_e32 v129, v128, v128
	v_lshlrev_b32_e32 v126, 16, v118
	v_and_b32_e32 v147, 0xffff0000, v119
	v_fmac_f32_e32 v129, v120, v120
	v_sub_f32_e32 v126, v128, v126
	v_sub_f32_e32 v146, v120, v146
	v_sub_f32_e32 v147, v121, v147
	v_fmac_f32_e32 v129, v121, v121
	v_cvt_pk_bf16_f32 v126, v126, v127
	v_cvt_pk_bf16_f32 v127, v146, v147
	v_add_f32_e32 v150, v178, v129
	v_lshlrev_b32_e32 v120, 16, v148
	v_lshlrev_b32_e32 v128, 16, v152
	v_and_b32_e32 v121, 0xffff0000, v148
	v_and_b32_e32 v129, 0xffff0000, v152
	v_lshlrev_b32_e32 v146, 16, v149
	v_lshlrev_b32_e32 v148, 16, v153
	v_and_b32_e32 v147, 0xffff0000, v149
	v_and_b32_e32 v149, 0xffff0000, v153
	v_pk_add_f32 v[120:121], v[120:121], v[128:129]
	v_pk_add_f32 v[128:129], v[146:147], v[148:149]
	v_pk_fma_f32 v[114:115], s[6:7], v[114:115], v[120:121]
	v_pk_fma_f32 v[116:117], s[60:61], v[116:117], v[128:129]
	v_cvt_pk_bf16_f32 v120, v114, v115
	s_nop 0
	v_and_b32_e32 v129, 0xffff0000, v120
	v_sub_f32_e32 v129, v115, v129
	v_mul_f32_e32 v115, v115, v115
	v_fmac_f32_e32 v115, v114, v114
	v_fmac_f32_e32 v115, v116, v116
	v_lshlrev_b32_e32 v128, 16, v120
	v_fmac_f32_e32 v115, v117, v117
	v_sub_f32_e32 v128, v114, v128
	v_add_f32_e32 v114, v150, v115
	v_mov_b32_e32 v115, v114
	s_nop 1
	v_permlane16_swap_b32_e32 v114, v115
	v_cvt_pk_bf16_f32 v121, v116, v117
	v_add_f32_e32 v114, v114, v115
	v_lshlrev_b32_e32 v146, 16, v121
	v_and_b32_e32 v147, 0xffff0000, v121
	v_sub_f32_e32 v146, v116, v146
	v_sub_f32_e32 v147, v117, v147
	v_mov_b32_e32 v115, v114
	v_cvt_pk_bf16_f32 v128, v128, v129
	v_cvt_pk_bf16_f32 v129, v146, v147
	s_nop 1
	v_permlane32_swap_b32_e32 v114, v115
	v_lshl_add_u64 v[146:147], v[168:169], 2, s[62:63]
	global_store_dwordx4 v[122:123], v[118:121], off offset:64
	global_store_dwordx4 v[124:125], v[126:129], off offset:64
	v_add_f32_e32 v246, v114, v115
	v_or_b32_e32 v114, 32, v168
	v_ashrrev_i32_e32 v115, 31, v114
	v_lshlrev_b64 v[114:115], 10, v[114:115]
	v_lshl_add_u64 v[114:115], v[114:115], 0, v[166:167]
	v_lshlrev_b64 v[148:149], 1, v[114:115]
	v_lshl_add_u64 v[114:115], s[68:69], 0, v[148:149]
	v_lshl_add_u64 v[118:119], s[88:89], 0, v[148:149]
	global_load_dwordx4 v[122:125], v[114:115], off
	s_nop 0
	global_load_dwordx4 v[114:117], v[114:115], off offset:64
	s_nop 0
	global_load_dwordx4 v[126:129], v[118:119], off
	s_nop 0
	global_load_dwordx4 v[118:121], v[118:119], off offset:64
	s_and_saveexec_b64 s[36:37], s[0:1]
	s_cbranch_execz .LBB0_871
	global_atomic_add_f32 v[146:147], v246, off
; template <int EPI>
; __device__ __forceinline__ void gemm_epilogue(const f32x4 (&acc)[2][2][4][2], const Unit& u, int wr, int wc, int fr, int fq,
;                                               const EpiArgs& ea, const float (&rs_pre)[2][4]) {
;     ...
;     for (int it = 0; it < 8; ++it) {
;       const int ai = it >> 2, m = it & 3;
;       if (it + 1 < 8) EPI_LOAD_ROW(it + 1, hn, ln_, pq);
;       const int row = row0 + ai * 128 + m * 16;
;       float sq = 0.f;
; #pragma unroll
;       for (int bj = 0; bj < 2; ++bj) {
;         const size_t idx = (size_t)row * 1024 + lcp + bj * 32;
;         const uint32_t hw[4] = {hc[bj].x, hc[bj].y, hc[bj].z, hc[bj].w};
;         const uint32_t lw[4] = {lc[bj].x, lc[bj].y, lc[bj].z, lc[bj].w};
;         const uint32_t pw[4] = {pc[bj].x, pc[bj].y, pc[bj].z, pc[bj].w};
;         uint32_t ho[4], lo_[4];
; #pragma unroll
;         for (int n = 0; n < 2; ++n) {
;           f32x4 xv;
;           xv[0] = __uint_as_float(hw[2 * n] << 16) + __uint_as_float(lw[2 * n] << 16);
;           xv[1] = __uint_as_float(hw[2 * n] & 0xffff0000u) + __uint_as_float(lw[2 * n] & 0xffff0000u);
;           xv[2] = __uint_as_float(hw[2 * n + 1] << 16) + __uint_as_float(lw[2 * n + 1] << 16);
;           xv[3] = __uint_as_float(hw[2 * n + 1] & 0xffff0000u) + __uint_as_float(lw[2 * n + 1] & 0xffff0000u);
;           const f32x4 a = acc[ai][bj][m][n];
;           f32x4 v;
;           if constexpr (EPI == EPI_PLEGATE) {
;             const float rs = rsr[ai][m], rpe = rper[ai][m];
;             const float pv[4] = {__uint_as_float(pw[2 * n] << 16), __uint_as_float(pw[2 * n] & 0xffff0000u),
;                                  __uint_as_float(pw[2 * n + 1] << 16), __uint_as_float(pw[2 * n + 1] & 0xffff0000u)};
; #pragma unroll
;             for (int i = 0; i < 4; ++i) v[i] = xv[i] + sigmoidf_(a[i] * rs) * (pv[i] * rpe);
;           } else {
;             v = xv + a * ea.alpha;
;           }
;           const uint2 hnew = pack4(v);
;           ho[2 * n] = hnew.x; ho[2 * n + 1] = hnew.y;
;           if (ea.xf32_out) {
;             *reinterpret_cast<f32x4*>(ea.xf32_out + idx + 4 * n) = v;
;           } else {
;             f32x4 r;
;             r[0] = v[0] - __uint_as_float(hnew.x << 16);
;             r[1] = v[1] - __uint_as_float(hnew.x & 0xffff0000u);
;             r[2] = v[2] - __uint_as_float(hnew.y << 16);
.LBB0_871:
	s_waitcnt vmcnt(9)
	s_or_b64 exec, exec, s[36:37]
	v_lshlrev_b32_e32 v150, 16, v138
	v_lshlrev_b32_e32 v152, 16, v142
	v_and_b32_e32 v151, 0xffff0000, v138
	v_and_b32_e32 v153, 0xffff0000, v142
	v_lshlrev_b32_e32 v138, 16, v139
	v_lshlrev_b32_e32 v142, 16, v143
	v_and_b32_e32 v139, 0xffff0000, v139
	v_and_b32_e32 v143, 0xffff0000, v143
	v_pk_add_f32 v[150:151], v[150:151], v[152:153]
	v_pk_add_f32 v[138:139], v[138:139], v[142:143]
	v_pk_fma_f32 v[142:143], s[6:7], v[108:109], v[150:151]
	v_pk_fma_f32 v[110:111], s[60:61], v[110:111], v[138:139]
	v_cvt_pk_bf16_f32 v108, v142, v143
	s_nop 0
	v_cvt_pk_bf16_f32 v109, v110, v111
	v_lshlrev_b32_e32 v138, 16, v108
	v_and_b32_e32 v139, 0xffff0000, v108
	v_lshlrev_b32_e32 v150, 16, v109
	v_sub_f32_e32 v138, v142, v138
	v_sub_f32_e32 v139, v143, v139
	v_sub_f32_e32 v150, v110, v150
	v_and_b32_e32 v151, 0xffff0000, v109
	v_sub_f32_e32 v151, v111, v151
	v_cvt_pk_bf16_f32 v138, v138, v139
	v_cvt_pk_bf16_f32 v139, v150, v151
	v_mul_f32_e32 v150, v143, v143
	v_fmac_f32_e32 v150, v142, v142
	v_fmac_f32_e32 v150, v110, v110
	v_fmac_f32_e32 v150, v111, v111
	v_lshlrev_b32_e32 v110, 16, v140
	v_lshlrev_b32_e32 v142, 16, v144
	v_and_b32_e32 v111, 0xffff0000, v140
	v_and_b32_e32 v143, 0xffff0000, v144
	v_lshlrev_b32_e32 v140, 16, v141
	v_lshlrev_b32_e32 v144, 16, v145
	v_and_b32_e32 v141, 0xffff0000, v141
	v_and_b32_e32 v145, 0xffff0000, v145
	v_pk_add_f32 v[110:111], v[110:111], v[142:143]
	v_pk_add_f32 v[140:141], v[140:141], v[144:145]
	v_pk_fma_f32 v[104:105], s[6:7], v[104:105], v[110:111]
	v_pk_fma_f32 v[106:107], s[60:61], v[106:107], v[140:141]
	v_cvt_pk_bf16_f32 v110, v104, v105
	s_nop 0
	v_and_b32_e32 v141, 0xffff0000, v110
	v_sub_f32_e32 v141, v105, v141
	v_mul_f32_e32 v105, v105, v105
	v_cvt_pk_bf16_f32 v111, v106, v107
	v_lshlrev_b32_e32 v140, 16, v110
	v_lshlrev_b32_e32 v142, 16, v111
	v_and_b32_e32 v143, 0xffff0000, v111
	v_fmac_f32_e32 v105, v104, v104
	v_sub_f32_e32 v140, v104, v140
	v_sub_f32_e32 v142, v106, v142
	v_sub_f32_e32 v143, v107, v143
	v_fmac_f32_e32 v105, v106, v106
	v_cvt_pk_bf16_f32 v140, v140, v141
	v_cvt_pk_bf16_f32 v141, v142, v143
	v_fmac_f32_e32 v105, v107, v107
	v_lshl_add_u64 v[142:143], s[46:47], 0, v[170:171]
	v_add_f32_e32 v144, v150, v105
	global_store_dwordx4 v[142:143], v[108:111], off
	v_lshlrev_b32_e32 v104, 16, v130
	v_lshlrev_b32_e32 v106, 16, v134
	v_and_b32_e32 v105, 0xffff0000, v130
	v_and_b32_e32 v107, 0xffff0000, v134
	v_lshlrev_b32_e32 v110, 16, v131
	v_lshlrev_b32_e32 v130, 16, v135
	v_and_b32_e32 v111, 0xffff0000, v131
	v_and_b32_e32 v131, 0xffff0000, v135
	v_pk_add_f32 v[104:105], v[104:105], v[106:107]
	v_pk_add_f32 v[106:107], v[110:111], v[130:131]
	v_lshlrev_b32_e32 v130, 16, v137
	v_pk_fma_f32 v[102:103], s[60:61], v[102:103], v[106:107]
	v_pk_fma_f32 v[106:107], s[6:7], v[100:101], v[104:105]
	v_cvt_pk_bf16_f32 v101, v102, v103
	v_and_b32_e32 v131, 0xffff0000, v137
	v_cvt_pk_bf16_f32 v100, v106, v107
	v_lshlrev_b32_e32 v110, 16, v101
	v_and_b32_e32 v105, 0xffff0000, v100
	v_sub_f32_e32 v105, v107, v105
	v_mul_f32_e32 v107, v107, v107
	v_fmac_f32_e32 v107, v106, v106
	v_lshlrev_b32_e32 v104, 16, v100
	v_and_b32_e32 v111, 0xffff0000, v101
	v_fmac_f32_e32 v107, v102, v102
	v_sub_f32_e32 v104, v106, v104
	v_sub_f32_e32 v110, v102, v110
	v_sub_f32_e32 v111, v103, v111
	v_fmac_f32_e32 v107, v103, v103
	v_cvt_pk_bf16_f32 v104, v104, v105
	v_cvt_pk_bf16_f32 v105, v110, v111
	v_add_f32_e32 v134, v144, v107
	v_lshlrev_b32_e32 v102, 16, v132
	v_lshlrev_b32_e32 v106, 16, v136
	v_and_b32_e32 v103, 0xffff0000, v132
	v_and_b32_e32 v107, 0xffff0000, v136
	v_lshlrev_b32_e32 v110, 16, v133
	v_and_b32_e32 v111, 0xffff0000, v133
	v_pk_add_f32 v[102:103], v[102:103], v[106:107]
	v_pk_add_f32 v[106:107], v[110:111], v[130:131]
	v_pk_fma_f32 v[96:97], s[6:7], v[96:97], v[102:103]
	v_pk_fma_f32 v[98:99], s[60:61], v[98:99], v[106:107]
	v_cvt_pk_bf16_f32 v102, v96, v97
	v_lshl_add_u64 v[108:109], s[70:71], 0, v[170:171]
	v_and_b32_e32 v107, 0xffff0000, v102
	v_sub_f32_e32 v107, v97, v107
	v_mul_f32_e32 v97, v97, v97
	v_fmac_f32_e32 v97, v96, v96
	v_fmac_f32_e32 v97, v98, v98
	v_lshlrev_b32_e32 v106, 16, v102
	v_fmac_f32_e32 v97, v99, v99
	v_sub_f32_e32 v106, v96, v106
	v_add_f32_e32 v96, v134, v97
	v_mov_b32_e32 v97, v96
	s_nop 1
	v_permlane16_swap_b32_e32 v96, v97
	v_add_f32_e32 v96, v96, v97
	v_mov_b32_e32 v97, v96
	v_cvt_pk_bf16_f32 v103, v98, v99
	s_nop 1
	v_permlane32_swap_b32_e32 v96, v97
	v_lshlrev_b32_e32 v110, 16, v103
	v_and_b32_e32 v111, 0xffff0000, v103
	global_store_dwordx4 v[108:109], v[138:141], off
	v_sub_f32_e32 v110, v98, v110
	v_sub_f32_e32 v111, v99, v111
	v_cvt_pk_bf16_f32 v106, v106, v107
	v_cvt_pk_bf16_f32 v107, v110, v111
	global_store_dwordx4 v[142:143], v[100:103], off offset:64
	global_store_dwordx4 v[108:109], v[104:107], off offset:64
	v_add_f32_e32 v246, v96, v97
	v_or_b32_e32 v96, 48, v168
	v_ashrrev_i32_e32 v97, 31, v96
	v_lshlrev_b64 v[96:97], 10, v[96:97]
	v_lshl_add_u64 v[96:97], v[96:97], 0, v[166:167]
	v_lshlrev_b64 v[130:131], 1, v[96:97]
	v_lshl_add_u64 v[96:97], s[68:69], 0, v[130:131]
	v_lshl_add_u64 v[100:101], s[88:89], 0, v[130:131]
	global_load_dwordx4 v[104:107], v[96:97], off
	s_nop 0
	global_load_dwordx4 v[96:99], v[96:97], off offset:64
	s_nop 0
	global_load_dwordx4 v[108:111], v[100:101], off
	s_nop 0
	global_load_dwordx4 v[100:103], v[100:101], off offset:64
	s_and_saveexec_b64 s[36:37], s[0:1]
	s_cbranch_execz .LBB0_873
	global_atomic_add_f32 v[146:147], v246, off offset:64
; template <int EPI>
; __device__ __forceinline__ void gemm_epilogue(const f32x4 (&acc)[2][2][4][2], const Unit& u, int wr, int wc, int fr, int fq,
;                                               const EpiArgs& ea, const float (&rs_pre)[2][4]) {
;     ...
;     for (int it = 0; it < 8; ++it) {
;       const int ai = it >> 2, m = it & 3;
;       if (it + 1 < 8) EPI_LOAD_ROW(it + 1, hn, ln_, pq);
;       const int row = row0 + ai * 128 + m * 16;
;       float sq = 0.f;
; #pragma unroll
;       for (int bj = 0; bj < 2; ++bj) {
;         const size_t idx = (size_t)row * 1024 + lcp + bj * 32;
;         const uint32_t hw[4] = {hc[bj].x, hc[bj].y, hc[bj].z, hc[bj].w};
;         const uint32_t lw[4] = {lc[bj].x, lc[bj].y, lc[bj].z, lc[bj].w};
;         const uint32_t pw[4] = {pc[bj].x, pc[bj].y, pc[bj].z, pc[bj].w};
;         uint32_t ho[4], lo_[4];
; #pragma unroll
;         for (int n = 0; n < 2; ++n) {
;           f32x4 xv;
;           xv[0] = __uint_as_float(hw[2 * n] << 16) + __uint_as_float(lw[2 * n] << 16);
;           xv[1] = __uint_as_float(hw[2 * n] & 0xffff0000u) + __uint_as_float(lw[2 * n] & 0xffff0000u);
;           xv[2] = __uint_as_float(hw[2 * n + 1] << 16) + __uint_as_float(lw[2 * n + 1] << 16);
;           xv[3] = __uint_as_float(hw[2 * n + 1] & 0xffff0000u) + __uint_as_float(lw[2 * n + 1] & 0xffff0000u);
;           const f32x4 a = acc[ai][bj][m][n];
;           f32x4 v;
;           if constexpr (EPI == EPI_PLEGATE) {
;             const float rs = rsr[ai][m], rpe = rper[ai][m];
;             const float pv[4] = {__uint_as_float(pw[2 * n] << 16), __uint_as_float(pw[2 * n] & 0xffff0000u),
;                                  __uint_as_float(pw[2 * n + 1] << 16), __uint_as_float(pw[2 * n + 1] & 0xffff0000u)};
; #pragma unroll
;             for (int i = 0; i < 4; ++i) v[i] = xv[i] + sigmoidf_(a[i] * rs) * (pv[i] * rpe);
;           } else {
;             v = xv + a * ea.alpha;
;           }
;           const uint2 hnew = pack4(v);
;           ho[2 * n] = hnew.x; ho[2 * n + 1] = hnew.y;
;           if (ea.xf32_out) {
;             *reinterpret_cast<f32x4*>(ea.xf32_out + idx + 4 * n) = v;
;           } else {
;             f32x4 r;
;             r[0] = v[0] - __uint_as_float(hnew.x << 16);
;             r[1] = v[1] - __uint_as_float(hnew.x & 0xffff0000u);
;             r[2] = v[2] - __uint_as_float(hnew.y << 16);
.LBB0_873:
	s_waitcnt vmcnt(10)
	s_or_b64 exec, exec, s[36:37]
	v_lshlrev_b32_e32 v132, 16, v122
	v_lshlrev_b32_e32 v134, 16, v126
	v_and_b32_e32 v133, 0xffff0000, v122
	v_and_b32_e32 v135, 0xffff0000, v126
	v_lshlrev_b32_e32 v122, 16, v123
	v_lshlrev_b32_e32 v126, 16, v127
	v_and_b32_e32 v123, 0xffff0000, v123
	v_and_b32_e32 v127, 0xffff0000, v127
	v_pk_add_f32 v[132:133], v[132:133], v[134:135]
	v_pk_add_f32 v[122:123], v[122:123], v[126:127]
	v_pk_fma_f32 v[126:127], s[6:7], v[92:93], v[132:133]
	v_pk_fma_f32 v[94:95], s[60:61], v[94:95], v[122:123]
	v_cvt_pk_bf16_f32 v92, v126, v127
	s_nop 0
	v_cvt_pk_bf16_f32 v93, v94, v95
	v_lshlrev_b32_e32 v122, 16, v92
	v_and_b32_e32 v123, 0xffff0000, v92
	v_lshlrev_b32_e32 v132, 16, v93
	v_sub_f32_e32 v122, v126, v122
	v_sub_f32_e32 v123, v127, v123
	v_sub_f32_e32 v132, v94, v132
	v_and_b32_e32 v133, 0xffff0000, v93
	v_sub_f32_e32 v133, v95, v133
	v_cvt_pk_bf16_f32 v122, v122, v123
	v_cvt_pk_bf16_f32 v123, v132, v133
	v_mul_f32_e32 v132, v127, v127
	v_fmac_f32_e32 v132, v126, v126
	v_fmac_f32_e32 v132, v94, v94
	v_fmac_f32_e32 v132, v95, v95
	v_lshlrev_b32_e32 v94, 16, v124
	v_lshlrev_b32_e32 v126, 16, v128
	v_and_b32_e32 v95, 0xffff0000, v124
	v_and_b32_e32 v127, 0xffff0000, v128
	v_lshlrev_b32_e32 v124, 16, v125
	v_lshlrev_b32_e32 v128, 16, v129
	v_and_b32_e32 v125, 0xffff0000, v125
	v_and_b32_e32 v129, 0xffff0000, v129
	v_pk_add_f32 v[94:95], v[94:95], v[126:127]
	v_pk_add_f32 v[124:125], v[124:125], v[128:129]
	v_pk_fma_f32 v[88:89], s[6:7], v[88:89], v[94:95]
	v_pk_fma_f32 v[90:91], s[60:61], v[90:91], v[124:125]
	v_cvt_pk_bf16_f32 v94, v88, v89
	s_nop 0
	v_and_b32_e32 v125, 0xffff0000, v94
	v_sub_f32_e32 v125, v89, v125
	v_mul_f32_e32 v89, v89, v89
	v_cvt_pk_bf16_f32 v95, v90, v91
	v_lshlrev_b32_e32 v124, 16, v94
	v_lshlrev_b32_e32 v126, 16, v95
	v_and_b32_e32 v127, 0xffff0000, v95
	v_fmac_f32_e32 v89, v88, v88
	v_sub_f32_e32 v124, v88, v124
	v_sub_f32_e32 v126, v90, v126
	v_sub_f32_e32 v127, v91, v127
	v_fmac_f32_e32 v89, v90, v90
	v_cvt_pk_bf16_f32 v124, v124, v125
	v_cvt_pk_bf16_f32 v125, v126, v127
	v_fmac_f32_e32 v89, v91, v91
	v_lshl_add_u64 v[126:127], s[46:47], 0, v[148:149]
	v_add_f32_e32 v128, v132, v89
	global_store_dwordx4 v[126:127], v[92:95], off
	v_lshlrev_b32_e32 v88, 16, v114
	v_lshlrev_b32_e32 v90, 16, v118
	v_and_b32_e32 v89, 0xffff0000, v114
	v_and_b32_e32 v91, 0xffff0000, v118
	v_lshlrev_b32_e32 v94, 16, v115
	v_lshlrev_b32_e32 v114, 16, v119
	v_and_b32_e32 v95, 0xffff0000, v115
	v_and_b32_e32 v115, 0xffff0000, v119
	v_pk_add_f32 v[88:89], v[88:89], v[90:91]
	v_pk_add_f32 v[90:91], v[94:95], v[114:115]
	v_lshlrev_b32_e32 v114, 16, v121
	v_pk_fma_f32 v[86:87], s[60:61], v[86:87], v[90:91]
	v_pk_fma_f32 v[90:91], s[6:7], v[84:85], v[88:89]
	v_cvt_pk_bf16_f32 v85, v86, v87
	v_and_b32_e32 v115, 0xffff0000, v121
	v_cvt_pk_bf16_f32 v84, v90, v91
	v_lshlrev_b32_e32 v94, 16, v85
	v_and_b32_e32 v89, 0xffff0000, v84
	v_sub_f32_e32 v89, v91, v89
	v_mul_f32_e32 v91, v91, v91
	v_fmac_f32_e32 v91, v90, v90
	v_lshlrev_b32_e32 v88, 16, v84
	v_and_b32_e32 v95, 0xffff0000, v85
	v_fmac_f32_e32 v91, v86, v86
	v_sub_f32_e32 v88, v90, v88
	v_sub_f32_e32 v94, v86, v94
	v_sub_f32_e32 v95, v87, v95
	v_fmac_f32_e32 v91, v87, v87
	v_cvt_pk_bf16_f32 v88, v88, v89
	v_cvt_pk_bf16_f32 v89, v94, v95
	v_add_f32_e32 v118, v128, v91
	v_lshlrev_b32_e32 v86, 16, v116
	v_lshlrev_b32_e32 v90, 16, v120
	v_and_b32_e32 v87, 0xffff0000, v116
	v_and_b32_e32 v91, 0xffff0000, v120
	v_lshlrev_b32_e32 v94, 16, v117
	v_and_b32_e32 v95, 0xffff0000, v117
	v_pk_add_f32 v[86:87], v[86:87], v[90:91]
	v_pk_add_f32 v[90:91], v[94:95], v[114:115]
	v_pk_fma_f32 v[80:81], s[6:7], v[80:81], v[86:87]
	v_pk_fma_f32 v[82:83], s[60:61], v[82:83], v[90:91]
	v_cvt_pk_bf16_f32 v86, v80, v81
	v_lshl_add_u64 v[92:93], s[70:71], 0, v[148:149]
	v_and_b32_e32 v91, 0xffff0000, v86
	v_sub_f32_e32 v91, v81, v91
	v_mul_f32_e32 v81, v81, v81
	v_fmac_f32_e32 v81, v80, v80
	v_fmac_f32_e32 v81, v82, v82
	v_lshlrev_b32_e32 v90, 16, v86
	v_fmac_f32_e32 v81, v83, v83
	v_sub_f32_e32 v90, v80, v90
	v_add_f32_e32 v80, v118, v81
	v_mov_b32_e32 v81, v80
	s_nop 1
	v_permlane16_swap_b32_e32 v80, v81
	v_add_f32_e32 v80, v80, v81
	v_mov_b32_e32 v81, v80
	v_cvt_pk_bf16_f32 v87, v82, v83
	s_nop 1
	v_permlane32_swap_b32_e32 v80, v81
	v_lshlrev_b32_e32 v94, 16, v87
	v_and_b32_e32 v95, 0xffff0000, v87
	global_store_dwordx4 v[92:93], v[122:125], off
	v_sub_f32_e32 v94, v82, v94
	v_sub_f32_e32 v95, v83, v95
	v_cvt_pk_bf16_f32 v90, v90, v91
	v_cvt_pk_bf16_f32 v91, v94, v95
	global_store_dwordx4 v[126:127], v[84:87], off offset:64
	global_store_dwordx4 v[92:93], v[88:91], off offset:64
	v_add_f32_e32 v246, v80, v81
	v_add_u32_e32 v114, 0x80, v168
	v_ashrrev_i32_e32 v115, 31, v114
	v_lshlrev_b64 v[80:81], 10, v[114:115]
	v_lshl_add_u64 v[80:81], v[80:81], 0, v[166:167]
	v_lshlrev_b64 v[116:117], 1, v[80:81]
	v_lshl_add_u64 v[80:81], s[68:69], 0, v[116:117]
	v_lshl_add_u64 v[84:85], s[88:89], 0, v[116:117]
	global_load_dwordx4 v[88:91], v[80:81], off
	s_nop 0
	global_load_dwordx4 v[80:83], v[80:81], off offset:64
	s_nop 0
	global_load_dwordx4 v[92:95], v[84:85], off
	s_nop 0
	global_load_dwordx4 v[84:87], v[84:85], off offset:64
	s_and_saveexec_b64 s[36:37], s[0:1]
	s_cbranch_execz .LBB0_875
	global_atomic_add_f32 v[146:147], v246, off offset:128
; template <int EPI>
; __device__ __forceinline__ void gemm_epilogue(const f32x4 (&acc)[2][2][4][2], const Unit& u, int wr, int wc, int fr, int fq,
;                                               const EpiArgs& ea, const float (&rs_pre)[2][4]) {
;     ...
;     for (int it = 0; it < 8; ++it) {
;       const int ai = it >> 2, m = it & 3;
;       if (it + 1 < 8) EPI_LOAD_ROW(it + 1, hn, ln_, pq);
;       const int row = row0 + ai * 128 + m * 16;
;       float sq = 0.f;
; #pragma unroll
;       for (int bj = 0; bj < 2; ++bj) {
;         const size_t idx = (size_t)row * 1024 + lcp + bj * 32;
;         const uint32_t hw[4] = {hc[bj].x, hc[bj].y, hc[bj].z, hc[bj].w};
;         const uint32_t lw[4] = {lc[bj].x, lc[bj].y, lc[bj].z, lc[bj].w};
;         const uint32_t pw[4] = {pc[bj].x, pc[bj].y, pc[bj].z, pc[bj].w};
;         uint32_t ho[4], lo_[4];
; #pragma unroll
;         for (int n = 0; n < 2; ++n) {
;           f32x4 xv;
;           xv[0] = __uint_as_float(hw[2 * n] << 16) + __uint_as_float(lw[2 * n] << 16);
;           xv[1] = __uint_as_float(hw[2 * n] & 0xffff0000u) + __uint_as_float(lw[2 * n] & 0xffff0000u);
;           xv[2] = __uint_as_float(hw[2 * n + 1] << 16) + __uint_as_float(lw[2 * n + 1] << 16);
;           xv[3] = __uint_as_float(hw[2 * n + 1] & 0xffff0000u) + __uint_as_float(lw[2 * n + 1] & 0xffff0000u);
;           const f32x4 a = acc[ai][bj][m][n];
;           f32x4 v;
;           if constexpr (EPI == EPI_PLEGATE) {
;             const float rs = rsr[ai][m], rpe = rper[ai][m];
;             const float pv[4] = {__uint_as_float(pw[2 * n] << 16), __uint_as_float(pw[2 * n] & 0xffff0000u),
;                                  __uint_as_float(pw[2 * n + 1] << 16), __uint_as_float(pw[2 * n + 1] & 0xffff0000u)};
; #pragma unroll
;             for (int i = 0; i < 4; ++i) v[i] = xv[i] + sigmoidf_(a[i] * rs) * (pv[i] * rpe);
;           } else {
;             v = xv + a * ea.alpha;
;           }
;           const uint2 hnew = pack4(v);
;           ho[2 * n] = hnew.x; ho[2 * n + 1] = hnew.y;
;           if (ea.xf32_out) {
;             *reinterpret_cast<f32x4*>(ea.xf32_out + idx + 4 * n) = v;
;           } else {
;             f32x4 r;
;             r[0] = v[0] - __uint_as_float(hnew.x << 16);
;             r[1] = v[1] - __uint_as_float(hnew.x & 0xffff0000u);
;             r[2] = v[2] - __uint_as_float(hnew.y << 16);
.LBB0_875:
	s_waitcnt vmcnt(10)
	s_or_b64 exec, exec, s[36:37]
	v_lshlrev_b32_e32 v118, 16, v104
	v_lshlrev_b32_e32 v120, 16, v108
	v_and_b32_e32 v119, 0xffff0000, v104
	v_and_b32_e32 v121, 0xffff0000, v108
	v_lshlrev_b32_e32 v104, 16, v105
	v_lshlrev_b32_e32 v108, 16, v109
	v_and_b32_e32 v105, 0xffff0000, v105
	v_and_b32_e32 v109, 0xffff0000, v109
	v_pk_add_f32 v[118:119], v[118:119], v[120:121]
	v_pk_add_f32 v[104:105], v[104:105], v[108:109]
	v_pk_fma_f32 v[108:109], s[6:7], v[76:77], v[118:119]
	v_pk_fma_f32 v[78:79], s[60:61], v[78:79], v[104:105]
	v_cvt_pk_bf16_f32 v76, v108, v109
	s_nop 0
	v_cvt_pk_bf16_f32 v77, v78, v79
	v_lshlrev_b32_e32 v104, 16, v76
	v_and_b32_e32 v105, 0xffff0000, v76
	v_lshlrev_b32_e32 v115, 16, v77
	v_sub_f32_e32 v104, v108, v104
	v_sub_f32_e32 v105, v109, v105
	v_sub_f32_e32 v115, v78, v115
	v_and_b32_e32 v118, 0xffff0000, v77
	v_sub_f32_e32 v118, v79, v118
	v_cvt_pk_bf16_f32 v104, v104, v105
	v_cvt_pk_bf16_f32 v105, v115, v118
	v_mul_f32_e32 v115, v109, v109
	v_fmac_f32_e32 v115, v108, v108
	v_fmac_f32_e32 v115, v78, v78
	v_fmac_f32_e32 v115, v79, v79
	v_lshlrev_b32_e32 v78, 16, v106
	v_lshlrev_b32_e32 v108, 16, v110
	v_and_b32_e32 v79, 0xffff0000, v106
	v_and_b32_e32 v109, 0xffff0000, v110
	v_lshlrev_b32_e32 v106, 16, v107
	v_lshlrev_b32_e32 v110, 16, v111
	v_and_b32_e32 v107, 0xffff0000, v107
	v_and_b32_e32 v111, 0xffff0000, v111
	v_pk_add_f32 v[78:79], v[78:79], v[108:109]
	v_pk_add_f32 v[106:107], v[106:107], v[110:111]
	v_pk_fma_f32 v[72:73], s[6:7], v[72:73], v[78:79]
	v_pk_fma_f32 v[74:75], s[60:61], v[74:75], v[106:107]
	v_cvt_pk_bf16_f32 v78, v72, v73
	s_nop 0
	v_and_b32_e32 v107, 0xffff0000, v78
	v_sub_f32_e32 v107, v73, v107
	v_mul_f32_e32 v73, v73, v73
	v_cvt_pk_bf16_f32 v79, v74, v75
	v_lshlrev_b32_e32 v106, 16, v78
	v_lshlrev_b32_e32 v108, 16, v79
	v_and_b32_e32 v109, 0xffff0000, v79
	v_fmac_f32_e32 v73, v72, v72
	v_sub_f32_e32 v106, v72, v106
	v_sub_f32_e32 v108, v74, v108
	v_sub_f32_e32 v109, v75, v109
	v_fmac_f32_e32 v73, v74, v74
	v_cvt_pk_bf16_f32 v106, v106, v107
	v_cvt_pk_bf16_f32 v107, v108, v109
	v_fmac_f32_e32 v73, v75, v75
	v_lshl_add_u64 v[108:109], s[46:47], 0, v[130:131]
	v_add_f32_e32 v110, v115, v73
	global_store_dwordx4 v[108:109], v[76:79], off
	v_lshlrev_b32_e32 v72, 16, v96
	v_lshlrev_b32_e32 v74, 16, v100
	v_and_b32_e32 v73, 0xffff0000, v96
	v_and_b32_e32 v75, 0xffff0000, v100
	v_lshlrev_b32_e32 v78, 16, v97
	v_lshlrev_b32_e32 v96, 16, v101
	v_and_b32_e32 v79, 0xffff0000, v97
	v_and_b32_e32 v97, 0xffff0000, v101
	v_pk_add_f32 v[72:73], v[72:73], v[74:75]
	v_pk_add_f32 v[74:75], v[78:79], v[96:97]
	v_lshlrev_b32_e32 v96, 16, v103
	v_pk_fma_f32 v[70:71], s[60:61], v[70:71], v[74:75]
	v_pk_fma_f32 v[74:75], s[6:7], v[68:69], v[72:73]
	v_cvt_pk_bf16_f32 v69, v70, v71
	v_and_b32_e32 v97, 0xffff0000, v103
	v_cvt_pk_bf16_f32 v68, v74, v75
	v_lshlrev_b32_e32 v78, 16, v69
	v_and_b32_e32 v73, 0xffff0000, v68
	v_sub_f32_e32 v73, v75, v73
	v_mul_f32_e32 v75, v75, v75
	v_fmac_f32_e32 v75, v74, v74
	v_lshlrev_b32_e32 v72, 16, v68
	v_and_b32_e32 v79, 0xffff0000, v69
	v_fmac_f32_e32 v75, v70, v70
	v_sub_f32_e32 v72, v74, v72
	v_sub_f32_e32 v78, v70, v78
	v_sub_f32_e32 v79, v71, v79
	v_fmac_f32_e32 v75, v71, v71
	v_cvt_pk_bf16_f32 v72, v72, v73
	v_cvt_pk_bf16_f32 v73, v78, v79
	v_add_f32_e32 v100, v110, v75
	v_lshlrev_b32_e32 v70, 16, v98
	v_lshlrev_b32_e32 v74, 16, v102
	v_and_b32_e32 v71, 0xffff0000, v98
	v_and_b32_e32 v75, 0xffff0000, v102
	v_lshlrev_b32_e32 v78, 16, v99
	v_and_b32_e32 v79, 0xffff0000, v99
	v_pk_add_f32 v[70:71], v[70:71], v[74:75]
	v_pk_add_f32 v[74:75], v[78:79], v[96:97]
	v_pk_fma_f32 v[64:65], s[6:7], v[64:65], v[70:71]
	v_pk_fma_f32 v[66:67], s[60:61], v[66:67], v[74:75]
	v_cvt_pk_bf16_f32 v70, v64, v65
	v_lshl_add_u64 v[76:77], s[70:71], 0, v[130:131]
	v_and_b32_e32 v75, 0xffff0000, v70
	v_sub_f32_e32 v75, v65, v75
	v_mul_f32_e32 v65, v65, v65
	v_fmac_f32_e32 v65, v64, v64
	v_fmac_f32_e32 v65, v66, v66
	v_lshlrev_b32_e32 v74, 16, v70
	v_fmac_f32_e32 v65, v67, v67
	v_sub_f32_e32 v74, v64, v74
	v_add_f32_e32 v64, v100, v65
	v_mov_b32_e32 v65, v64
	s_nop 1
	v_permlane16_swap_b32_e32 v64, v65
	v_add_f32_e32 v64, v64, v65
	v_mov_b32_e32 v65, v64
	v_cvt_pk_bf16_f32 v71, v66, v67
	s_nop 1
	v_permlane32_swap_b32_e32 v64, v65
	v_lshlrev_b32_e32 v78, 16, v71
	v_and_b32_e32 v79, 0xffff0000, v71
	global_store_dwordx4 v[76:77], v[104:107], off
	v_sub_f32_e32 v78, v66, v78
	v_sub_f32_e32 v79, v67, v79
	v_cvt_pk_bf16_f32 v74, v74, v75
	v_cvt_pk_bf16_f32 v75, v78, v79
	global_store_dwordx4 v[108:109], v[68:71], off offset:64
	global_store_dwordx4 v[76:77], v[72:75], off offset:64
	v_add_f32_e32 v246, v64, v65
	v_or_b32_e32 v64, 16, v114
	v_ashrrev_i32_e32 v65, 31, v64
	v_lshlrev_b64 v[64:65], 10, v[64:65]
	v_lshl_add_u64 v[64:65], v[64:65], 0, v[166:167]
	v_lshlrev_b64 v[96:97], 1, v[64:65]
	v_lshl_add_u64 v[64:65], s[68:69], 0, v[96:97]
	v_lshl_add_u64 v[68:69], s[88:89], 0, v[96:97]
	global_load_dwordx4 v[72:75], v[64:65], off
	s_nop 0
	global_load_dwordx4 v[64:67], v[64:65], off offset:64
	s_nop 0
	global_load_dwordx4 v[76:79], v[68:69], off
	s_nop 0
	global_load_dwordx4 v[68:71], v[68:69], off offset:64
	s_and_saveexec_b64 s[36:37], s[0:1]
	s_cbranch_execz .LBB0_877
	global_atomic_add_f32 v[146:147], v246, off offset:192
; template <int EPI>
; __device__ __forceinline__ void gemm_epilogue(const f32x4 (&acc)[2][2][4][2], const Unit& u, int wr, int wc, int fr, int fq,
;                                               const EpiArgs& ea, const float (&rs_pre)[2][4]) {
;     ...
;     for (int it = 0; it < 8; ++it) {
;       const int ai = it >> 2, m = it & 3;
;       if (it + 1 < 8) EPI_LOAD_ROW(it + 1, hn, ln_, pq);
;       const int row = row0 + ai * 128 + m * 16;
;       float sq = 0.f;
; #pragma unroll
;       for (int bj = 0; bj < 2; ++bj) {
;         const size_t idx = (size_t)row * 1024 + lcp + bj * 32;
;         const uint32_t hw[4] = {hc[bj].x, hc[bj].y, hc[bj].z, hc[bj].w};
;         const uint32_t lw[4] = {lc[bj].x, lc[bj].y, lc[bj].z, lc[bj].w};
;         const uint32_t pw[4] = {pc[bj].x, pc[bj].y, pc[bj].z, pc[bj].w};
;         uint32_t ho[4], lo_[4];
; #pragma unroll
;         for (int n = 0; n < 2; ++n) {
;           f32x4 xv;
;           xv[0] = __uint_as_float(hw[2 * n] << 16) + __uint_as_float(lw[2 * n] << 16);
;           xv[1] = __uint_as_float(hw[2 * n] & 0xffff0000u) + __uint_as_float(lw[2 * n] & 0xffff0000u);
;           xv[2] = __uint_as_float(hw[2 * n + 1] << 16) + __uint_as_float(lw[2 * n + 1] << 16);
;           xv[3] = __uint_as_float(hw[2 * n + 1] & 0xffff0000u) + __uint_as_float(lw[2 * n + 1] & 0xffff0000u);
;           const f32x4 a = acc[ai][bj][m][n];
;           f32x4 v;
;           if constexpr (EPI == EPI_PLEGATE) {
;             const float rs = rsr[ai][m], rpe = rper[ai][m];
;             const float pv[4] = {__uint_as_float(pw[2 * n] << 16), __uint_as_float(pw[2 * n] & 0xffff0000u),
;                                  __uint_as_float(pw[2 * n + 1] << 16), __uint_as_float(pw[2 * n + 1] & 0xffff0000u)};
; #pragma unroll
;             for (int i = 0; i < 4; ++i) v[i] = xv[i] + sigmoidf_(a[i] * rs) * (pv[i] * rpe);
;           } else {
;             v = xv + a * ea.alpha;
;           }
;           const uint2 hnew = pack4(v);
;           ho[2 * n] = hnew.x; ho[2 * n + 1] = hnew.y;
;           if (ea.xf32_out) {
;             *reinterpret_cast<f32x4*>(ea.xf32_out + idx + 4 * n) = v;
;           } else {
;             f32x4 r;
;             r[0] = v[0] - __uint_as_float(hnew.x << 16);
;             r[1] = v[1] - __uint_as_float(hnew.x & 0xffff0000u);
;             r[2] = v[2] - __uint_as_float(hnew.y << 16);
.LBB0_877:
	s_waitcnt vmcnt(10)
	s_or_b64 exec, exec, s[36:37]
	v_lshlrev_b32_e32 v98, 16, v88
	v_lshlrev_b32_e32 v100, 16, v92
	v_and_b32_e32 v99, 0xffff0000, v88
	v_and_b32_e32 v101, 0xffff0000, v92
	v_lshlrev_b32_e32 v88, 16, v89
	v_lshlrev_b32_e32 v92, 16, v93
	v_and_b32_e32 v89, 0xffff0000, v89
	v_and_b32_e32 v93, 0xffff0000, v93
	v_pk_add_f32 v[98:99], v[98:99], v[100:101]
	v_pk_add_f32 v[88:89], v[88:89], v[92:93]
	v_pk_fma_f32 v[92:93], s[6:7], v[60:61], v[98:99]
	v_pk_fma_f32 v[62:63], s[60:61], v[62:63], v[88:89]
	v_cvt_pk_bf16_f32 v60, v92, v93
	s_nop 0
	v_cvt_pk_bf16_f32 v61, v62, v63
	v_lshlrev_b32_e32 v88, 16, v60
	v_and_b32_e32 v89, 0xffff0000, v60
	v_lshlrev_b32_e32 v98, 16, v61
	v_sub_f32_e32 v88, v92, v88
	v_sub_f32_e32 v89, v93, v89
	v_sub_f32_e32 v98, v62, v98
	v_and_b32_e32 v99, 0xffff0000, v61
	v_sub_f32_e32 v99, v63, v99
	v_cvt_pk_bf16_f32 v88, v88, v89
	v_cvt_pk_bf16_f32 v89, v98, v99
	v_mul_f32_e32 v98, v93, v93
	v_fmac_f32_e32 v98, v92, v92
	v_fmac_f32_e32 v98, v62, v62
	v_fmac_f32_e32 v98, v63, v63
	v_lshlrev_b32_e32 v62, 16, v90
	v_lshlrev_b32_e32 v92, 16, v94
	v_and_b32_e32 v63, 0xffff0000, v90
	v_and_b32_e32 v93, 0xffff0000, v94
	v_lshlrev_b32_e32 v90, 16, v91
	v_lshlrev_b32_e32 v94, 16, v95
	v_and_b32_e32 v91, 0xffff0000, v91
	v_and_b32_e32 v95, 0xffff0000, v95
	v_pk_add_f32 v[62:63], v[62:63], v[92:93]
	v_pk_add_f32 v[90:91], v[90:91], v[94:95]
	v_pk_fma_f32 v[56:57], s[6:7], v[56:57], v[62:63]
	v_pk_fma_f32 v[58:59], s[60:61], v[58:59], v[90:91]
	v_cvt_pk_bf16_f32 v62, v56, v57
	s_nop 0
	v_and_b32_e32 v91, 0xffff0000, v62
	v_sub_f32_e32 v91, v57, v91
	v_mul_f32_e32 v57, v57, v57
	v_cvt_pk_bf16_f32 v63, v58, v59
	v_lshlrev_b32_e32 v90, 16, v62
	v_lshlrev_b32_e32 v92, 16, v63
	v_and_b32_e32 v93, 0xffff0000, v63
	v_fmac_f32_e32 v57, v56, v56
	v_sub_f32_e32 v90, v56, v90
	v_sub_f32_e32 v92, v58, v92
	v_sub_f32_e32 v93, v59, v93
	v_fmac_f32_e32 v57, v58, v58
	v_cvt_pk_bf16_f32 v90, v90, v91
	v_cvt_pk_bf16_f32 v91, v92, v93
	v_fmac_f32_e32 v57, v59, v59
	v_lshl_add_u64 v[92:93], s[46:47], 0, v[116:117]
	v_add_f32_e32 v94, v98, v57
	global_store_dwordx4 v[92:93], v[60:63], off
	v_lshlrev_b32_e32 v56, 16, v80
	v_lshlrev_b32_e32 v58, 16, v84
	v_and_b32_e32 v57, 0xffff0000, v80
	v_and_b32_e32 v59, 0xffff0000, v84
	v_lshlrev_b32_e32 v62, 16, v81
	v_lshlrev_b32_e32 v80, 16, v85
	v_and_b32_e32 v63, 0xffff0000, v81
	v_and_b32_e32 v81, 0xffff0000, v85
	v_pk_add_f32 v[56:57], v[56:57], v[58:59]
	v_pk_add_f32 v[58:59], v[62:63], v[80:81]
	v_lshlrev_b32_e32 v80, 16, v87
	v_pk_fma_f32 v[54:55], s[60:61], v[54:55], v[58:59]
	v_pk_fma_f32 v[58:59], s[6:7], v[52:53], v[56:57]
	v_cvt_pk_bf16_f32 v53, v54, v55
	v_and_b32_e32 v81, 0xffff0000, v87
	v_cvt_pk_bf16_f32 v52, v58, v59
	v_lshlrev_b32_e32 v62, 16, v53
	v_and_b32_e32 v57, 0xffff0000, v52
	v_sub_f32_e32 v57, v59, v57
	v_mul_f32_e32 v59, v59, v59
	v_fmac_f32_e32 v59, v58, v58
	v_lshlrev_b32_e32 v56, 16, v52
	v_and_b32_e32 v63, 0xffff0000, v53
	v_fmac_f32_e32 v59, v54, v54
	v_sub_f32_e32 v56, v58, v56
	v_sub_f32_e32 v62, v54, v62
	v_sub_f32_e32 v63, v55, v63
	v_fmac_f32_e32 v59, v55, v55
	v_cvt_pk_bf16_f32 v56, v56, v57
	v_cvt_pk_bf16_f32 v57, v62, v63
	v_add_f32_e32 v84, v94, v59
	v_lshlrev_b32_e32 v54, 16, v82
	v_lshlrev_b32_e32 v58, 16, v86
	v_and_b32_e32 v55, 0xffff0000, v82
	v_and_b32_e32 v59, 0xffff0000, v86
	v_lshlrev_b32_e32 v62, 16, v83
	v_and_b32_e32 v63, 0xffff0000, v83
	v_pk_add_f32 v[54:55], v[54:55], v[58:59]
	v_pk_add_f32 v[58:59], v[62:63], v[80:81]
	v_pk_fma_f32 v[48:49], s[6:7], v[48:49], v[54:55]
	v_pk_fma_f32 v[50:51], s[60:61], v[50:51], v[58:59]
	v_cvt_pk_bf16_f32 v54, v48, v49
	v_lshl_add_u64 v[60:61], s[70:71], 0, v[116:117]
	v_and_b32_e32 v59, 0xffff0000, v54
	v_sub_f32_e32 v59, v49, v59
	v_mul_f32_e32 v49, v49, v49
	v_fmac_f32_e32 v49, v48, v48
	v_fmac_f32_e32 v49, v50, v50
	v_lshlrev_b32_e32 v58, 16, v54
	v_fmac_f32_e32 v49, v51, v51
	v_sub_f32_e32 v58, v48, v58
	v_add_f32_e32 v48, v84, v49
	v_mov_b32_e32 v49, v48
	s_nop 1
	v_permlane16_swap_b32_e32 v48, v49
	v_add_f32_e32 v48, v48, v49
	v_mov_b32_e32 v49, v48
	v_cvt_pk_bf16_f32 v55, v50, v51
	s_nop 1
	v_permlane32_swap_b32_e32 v48, v49
	v_lshlrev_b32_e32 v62, 16, v55
	v_and_b32_e32 v63, 0xffff0000, v55
	global_store_dwordx4 v[60:61], v[88:91], off
	v_sub_f32_e32 v62, v50, v62
	v_sub_f32_e32 v63, v51, v63
	v_cvt_pk_bf16_f32 v58, v58, v59
	v_cvt_pk_bf16_f32 v59, v62, v63
	global_store_dwordx4 v[92:93], v[52:55], off offset:64
	global_store_dwordx4 v[60:61], v[56:59], off offset:64
	v_add_f32_e32 v246, v48, v49
	v_or_b32_e32 v48, 32, v114
	v_ashrrev_i32_e32 v49, 31, v48
	v_lshlrev_b64 v[48:49], 10, v[48:49]
	v_lshl_add_u64 v[48:49], v[48:49], 0, v[166:167]
	v_lshlrev_b64 v[80:81], 1, v[48:49]
	v_lshl_add_u64 v[48:49], s[68:69], 0, v[80:81]
	v_lshl_add_u64 v[52:53], s[88:89], 0, v[80:81]
	global_load_dwordx4 v[56:59], v[48:49], off
	s_nop 0
	global_load_dwordx4 v[48:51], v[48:49], off offset:64
	s_nop 0
	global_load_dwordx4 v[60:63], v[52:53], off
	s_nop 0
	global_load_dwordx4 v[52:55], v[52:53], off offset:64
	s_and_saveexec_b64 s[36:37], s[0:1]
	s_cbranch_execz .LBB0_879
	global_atomic_add_f32 v[146:147], v246, off offset:512
; template <int EPI>
; __device__ __forceinline__ void gemm_epilogue(const f32x4 (&acc)[2][2][4][2], const Unit& u, int wr, int wc, int fr, int fq,
;                                               const EpiArgs& ea, const float (&rs_pre)[2][4]) {
;     ...
;     for (int it = 0; it < 8; ++it) {
;       const int ai = it >> 2, m = it & 3;
;       if (it + 1 < 8) EPI_LOAD_ROW(it + 1, hn, ln_, pq);
;       const int row = row0 + ai * 128 + m * 16;
;       float sq = 0.f;
; #pragma unroll
;       for (int bj = 0; bj < 2; ++bj) {
;         const size_t idx = (size_t)row * 1024 + lcp + bj * 32;
;         const uint32_t hw[4] = {hc[bj].x, hc[bj].y, hc[bj].z, hc[bj].w};
;         const uint32_t lw[4] = {lc[bj].x, lc[bj].y, lc[bj].z, lc[bj].w};
;         const uint32_t pw[4] = {pc[bj].x, pc[bj].y, pc[bj].z, pc[bj].w};
;         uint32_t ho[4], lo_[4];
; #pragma unroll
;         for (int n = 0; n < 2; ++n) {
;           f32x4 xv;
;           xv[0] = __uint_as_float(hw[2 * n] << 16) + __uint_as_float(lw[2 * n] << 16);
;           xv[1] = __uint_as_float(hw[2 * n] & 0xffff0000u) + __uint_as_float(lw[2 * n] & 0xffff0000u);
;           xv[2] = __uint_as_float(hw[2 * n + 1] << 16) + __uint_as_float(lw[2 * n + 1] << 16);
;           xv[3] = __uint_as_float(hw[2 * n + 1] & 0xffff0000u) + __uint_as_float(lw[2 * n + 1] & 0xffff0000u);
;           const f32x4 a = acc[ai][bj][m][n];
;           f32x4 v;
;           if constexpr (EPI == EPI_PLEGATE) {
;             const float rs = rsr[ai][m], rpe = rper[ai][m];
;             const float pv[4] = {__uint_as_float(pw[2 * n] << 16), __uint_as_float(pw[2 * n] & 0xffff0000u),
;                                  __uint_as_float(pw[2 * n + 1] << 16), __uint_as_float(pw[2 * n + 1] & 0xffff0000u)};
; #pragma unroll
;             for (int i = 0; i < 4; ++i) v[i] = xv[i] + sigmoidf_(a[i] * rs) * (pv[i] * rpe);
;           } else {
;             v = xv + a * ea.alpha;
;           }
;           const uint2 hnew = pack4(v);
;           ho[2 * n] = hnew.x; ho[2 * n + 1] = hnew.y;
;           if (ea.xf32_out) {
;             *reinterpret_cast<f32x4*>(ea.xf32_out + idx + 4 * n) = v;
;           } else {
;             f32x4 r;
;             r[0] = v[0] - __uint_as_float(hnew.x << 16);
;             r[1] = v[1] - __uint_as_float(hnew.x & 0xffff0000u);
;             r[2] = v[2] - __uint_as_float(hnew.y << 16);
.LBB0_879:
	s_waitcnt vmcnt(10)
	s_or_b64 exec, exec, s[36:37]
	v_lshlrev_b32_e32 v82, 16, v72
	v_lshlrev_b32_e32 v84, 16, v76
	v_and_b32_e32 v83, 0xffff0000, v72
	v_and_b32_e32 v85, 0xffff0000, v76
	v_lshlrev_b32_e32 v72, 16, v73
	v_lshlrev_b32_e32 v76, 16, v77
	v_and_b32_e32 v73, 0xffff0000, v73
	v_and_b32_e32 v77, 0xffff0000, v77
	v_pk_add_f32 v[82:83], v[82:83], v[84:85]
	v_pk_add_f32 v[72:73], v[72:73], v[76:77]
	v_pk_fma_f32 v[76:77], s[6:7], v[44:45], v[82:83]
	v_pk_fma_f32 v[46:47], s[60:61], v[46:47], v[72:73]
	v_cvt_pk_bf16_f32 v44, v76, v77
	s_nop 0
	v_cvt_pk_bf16_f32 v45, v46, v47
	v_lshlrev_b32_e32 v72, 16, v44
	v_and_b32_e32 v73, 0xffff0000, v44
	v_lshlrev_b32_e32 v82, 16, v45
	v_sub_f32_e32 v72, v76, v72
	v_sub_f32_e32 v73, v77, v73
	v_sub_f32_e32 v82, v46, v82
	v_and_b32_e32 v83, 0xffff0000, v45
	v_sub_f32_e32 v83, v47, v83
	v_cvt_pk_bf16_f32 v72, v72, v73
	v_cvt_pk_bf16_f32 v73, v82, v83
	v_mul_f32_e32 v82, v77, v77
	v_fmac_f32_e32 v82, v76, v76
	v_fmac_f32_e32 v82, v46, v46
	v_fmac_f32_e32 v82, v47, v47
	v_lshlrev_b32_e32 v46, 16, v74
	v_lshlrev_b32_e32 v76, 16, v78
	v_and_b32_e32 v47, 0xffff0000, v74
	v_and_b32_e32 v77, 0xffff0000, v78
	v_lshlrev_b32_e32 v74, 16, v75
	v_lshlrev_b32_e32 v78, 16, v79
	v_and_b32_e32 v75, 0xffff0000, v75
	v_and_b32_e32 v79, 0xffff0000, v79
	v_pk_add_f32 v[46:47], v[46:47], v[76:77]
	v_pk_add_f32 v[74:75], v[74:75], v[78:79]
	v_pk_fma_f32 v[40:41], s[6:7], v[40:41], v[46:47]
	v_pk_fma_f32 v[42:43], s[60:61], v[42:43], v[74:75]
	v_cvt_pk_bf16_f32 v46, v40, v41
	s_nop 0
	v_and_b32_e32 v75, 0xffff0000, v46
	v_sub_f32_e32 v75, v41, v75
	v_mul_f32_e32 v41, v41, v41
	v_cvt_pk_bf16_f32 v47, v42, v43
	v_lshlrev_b32_e32 v74, 16, v46
	v_lshlrev_b32_e32 v76, 16, v47
	v_and_b32_e32 v77, 0xffff0000, v47
	v_fmac_f32_e32 v41, v40, v40
	v_sub_f32_e32 v74, v40, v74
	v_sub_f32_e32 v76, v42, v76
	v_sub_f32_e32 v77, v43, v77
	v_fmac_f32_e32 v41, v42, v42
	v_cvt_pk_bf16_f32 v74, v74, v75
	v_cvt_pk_bf16_f32 v75, v76, v77
	v_fmac_f32_e32 v41, v43, v43
	v_lshl_add_u64 v[76:77], s[46:47], 0, v[96:97]
	v_add_f32_e32 v78, v82, v41
	global_store_dwordx4 v[76:77], v[44:47], off
	v_lshlrev_b32_e32 v40, 16, v64
	v_lshlrev_b32_e32 v42, 16, v68
	v_and_b32_e32 v41, 0xffff0000, v64
	v_and_b32_e32 v43, 0xffff0000, v68
	v_lshlrev_b32_e32 v46, 16, v65
	v_lshlrev_b32_e32 v64, 16, v69
	v_and_b32_e32 v47, 0xffff0000, v65
	v_and_b32_e32 v65, 0xffff0000, v69
	v_pk_add_f32 v[40:41], v[40:41], v[42:43]
	v_pk_add_f32 v[42:43], v[46:47], v[64:65]
	v_lshlrev_b32_e32 v64, 16, v71
	v_pk_fma_f32 v[38:39], s[60:61], v[38:39], v[42:43]
	v_pk_fma_f32 v[42:43], s[6:7], v[36:37], v[40:41]
	v_cvt_pk_bf16_f32 v37, v38, v39
	v_and_b32_e32 v65, 0xffff0000, v71
	v_cvt_pk_bf16_f32 v36, v42, v43
	v_lshlrev_b32_e32 v46, 16, v37
	v_and_b32_e32 v41, 0xffff0000, v36
	v_sub_f32_e32 v41, v43, v41
	v_mul_f32_e32 v43, v43, v43
	v_fmac_f32_e32 v43, v42, v42
	v_lshlrev_b32_e32 v40, 16, v36
	v_and_b32_e32 v47, 0xffff0000, v37
	v_fmac_f32_e32 v43, v38, v38
	v_sub_f32_e32 v40, v42, v40
	v_sub_f32_e32 v46, v38, v46
	v_sub_f32_e32 v47, v39, v47
	v_fmac_f32_e32 v43, v39, v39
	v_cvt_pk_bf16_f32 v40, v40, v41
	v_cvt_pk_bf16_f32 v41, v46, v47
	v_add_f32_e32 v68, v78, v43
	v_lshlrev_b32_e32 v38, 16, v66
	v_lshlrev_b32_e32 v42, 16, v70
	v_and_b32_e32 v39, 0xffff0000, v66
	v_and_b32_e32 v43, 0xffff0000, v70
	v_lshlrev_b32_e32 v46, 16, v67
	v_and_b32_e32 v47, 0xffff0000, v67
	v_pk_add_f32 v[38:39], v[38:39], v[42:43]
	v_pk_add_f32 v[42:43], v[46:47], v[64:65]
	v_pk_fma_f32 v[32:33], s[6:7], v[32:33], v[38:39]
	v_pk_fma_f32 v[34:35], s[60:61], v[34:35], v[42:43]
	v_cvt_pk_bf16_f32 v38, v32, v33
	v_lshl_add_u64 v[44:45], s[70:71], 0, v[96:97]
	v_and_b32_e32 v43, 0xffff0000, v38
	v_sub_f32_e32 v43, v33, v43
	v_mul_f32_e32 v33, v33, v33
	v_fmac_f32_e32 v33, v32, v32
	v_fmac_f32_e32 v33, v34, v34
	v_lshlrev_b32_e32 v42, 16, v38
	v_fmac_f32_e32 v33, v35, v35
	v_sub_f32_e32 v42, v32, v42
	v_add_f32_e32 v32, v68, v33
	v_mov_b32_e32 v33, v32
	s_nop 1
	v_permlane16_swap_b32_e32 v32, v33
	v_add_f32_e32 v32, v32, v33
	v_mov_b32_e32 v33, v32
	v_cvt_pk_bf16_f32 v39, v34, v35
	s_nop 1
	v_permlane32_swap_b32_e32 v32, v33
	v_lshlrev_b32_e32 v46, 16, v39
	v_and_b32_e32 v47, 0xffff0000, v39
	global_store_dwordx4 v[44:45], v[72:75], off
	v_sub_f32_e32 v46, v34, v46
	v_sub_f32_e32 v47, v35, v47
	v_cvt_pk_bf16_f32 v42, v42, v43
	v_cvt_pk_bf16_f32 v43, v46, v47
	global_store_dwordx4 v[76:77], v[36:39], off offset:64
	global_store_dwordx4 v[44:45], v[40:43], off offset:64
	v_add_f32_e32 v246, v32, v33
	v_or_b32_e32 v32, 48, v114
	v_ashrrev_i32_e32 v33, 31, v32
	v_lshlrev_b64 v[32:33], 10, v[32:33]
	v_lshl_add_u64 v[32:33], v[32:33], 0, v[166:167]
	v_lshlrev_b64 v[64:65], 1, v[32:33]
	v_lshl_add_u64 v[32:33], s[68:69], 0, v[64:65]
	v_lshl_add_u64 v[36:37], s[88:89], 0, v[64:65]
	global_load_dwordx4 v[40:43], v[32:33], off
	s_nop 0
	global_load_dwordx4 v[32:35], v[32:33], off offset:64
	s_nop 0
	global_load_dwordx4 v[44:47], v[36:37], off
	s_nop 0
	global_load_dwordx4 v[36:39], v[36:37], off offset:64
	s_and_saveexec_b64 s[36:37], s[0:1]
	s_cbranch_execz .LBB0_881
	global_atomic_add_f32 v[146:147], v246, off offset:576
; template <int EPI>
; __device__ __forceinline__ void gemm_epilogue(const f32x4 (&acc)[2][2][4][2], const Unit& u, int wr, int wc, int fr, int fq,
;                                               const EpiArgs& ea, const float (&rs_pre)[2][4]) {
;     ...
;     for (int it = 0; it < 8; ++it) {
;       const int ai = it >> 2, m = it & 3;
;       if (it + 1 < 8) EPI_LOAD_ROW(it + 1, hn, ln_, pq);
;       const int row = row0 + ai * 128 + m * 16;
;       float sq = 0.f;
; #pragma unroll
;       for (int bj = 0; bj < 2; ++bj) {
;         const size_t idx = (size_t)row * 1024 + lcp + bj * 32;
;         const uint32_t hw[4] = {hc[bj].x, hc[bj].y, hc[bj].z, hc[bj].w};
;         const uint32_t lw[4] = {lc[bj].x, lc[bj].y, lc[bj].z, lc[bj].w};
;         const uint32_t pw[4] = {pc[bj].x, pc[bj].y, pc[bj].z, pc[bj].w};
;         uint32_t ho[4], lo_[4];
; #pragma unroll
;         for (int n = 0; n < 2; ++n) {
;           f32x4 xv;
;           xv[0] = __uint_as_float(hw[2 * n] << 16) + __uint_as_float(lw[2 * n] << 16);
;           xv[1] = __uint_as_float(hw[2 * n] & 0xffff0000u) + __uint_as_float(lw[2 * n] & 0xffff0000u);
;           xv[2] = __uint_as_float(hw[2 * n + 1] << 16) + __uint_as_float(lw[2 * n + 1] << 16);
;           xv[3] = __uint_as_float(hw[2 * n + 1] & 0xffff0000u) + __uint_as_float(lw[2 * n + 1] & 0xffff0000u);
;           const f32x4 a = acc[ai][bj][m][n];
;           f32x4 v;
;           if constexpr (EPI == EPI_PLEGATE) {
;             const float rs = rsr[ai][m], rpe = rper[ai][m];
;             const float pv[4] = {__uint_as_float(pw[2 * n] << 16), __uint_as_float(pw[2 * n] & 0xffff0000u),
;                                  __uint_as_float(pw[2 * n + 1] << 16), __uint_as_float(pw[2 * n + 1] & 0xffff0000u)};
; #pragma unroll
;             for (int i = 0; i < 4; ++i) v[i] = xv[i] + sigmoidf_(a[i] * rs) * (pv[i] * rpe);
;           } else {
;             v = xv + a * ea.alpha;
;           }
;           const uint2 hnew = pack4(v);
;           ho[2 * n] = hnew.x; ho[2 * n + 1] = hnew.y;
;           if (ea.xf32_out) {
;             *reinterpret_cast<f32x4*>(ea.xf32_out + idx + 4 * n) = v;
;           } else {
;             f32x4 r;
;             r[0] = v[0] - __uint_as_float(hnew.x << 16);
;             r[1] = v[1] - __uint_as_float(hnew.x & 0xffff0000u);
;             r[2] = v[2] - __uint_as_float(hnew.y << 16);
.LBB0_881:
	s_waitcnt vmcnt(10)
	s_or_b64 exec, exec, s[36:37]
	v_lshlrev_b32_e32 v66, 16, v56
	v_lshlrev_b32_e32 v68, 16, v60
	v_and_b32_e32 v67, 0xffff0000, v56
	v_and_b32_e32 v69, 0xffff0000, v60
	v_lshlrev_b32_e32 v56, 16, v57
	v_lshlrev_b32_e32 v60, 16, v61
	v_and_b32_e32 v57, 0xffff0000, v57
	v_and_b32_e32 v61, 0xffff0000, v61
	v_pk_add_f32 v[66:67], v[66:67], v[68:69]
	v_pk_add_f32 v[56:57], v[56:57], v[60:61]
	v_pk_fma_f32 v[60:61], s[6:7], v[28:29], v[66:67]
	v_pk_fma_f32 v[30:31], s[60:61], v[30:31], v[56:57]
	v_cvt_pk_bf16_f32 v28, v60, v61
	s_nop 0
	v_cvt_pk_bf16_f32 v29, v30, v31
	v_lshlrev_b32_e32 v56, 16, v28
	v_and_b32_e32 v57, 0xffff0000, v28
	v_lshlrev_b32_e32 v66, 16, v29
	v_sub_f32_e32 v56, v60, v56
	v_sub_f32_e32 v57, v61, v57
	v_sub_f32_e32 v66, v30, v66
	v_and_b32_e32 v67, 0xffff0000, v29
	v_sub_f32_e32 v67, v31, v67
	v_cvt_pk_bf16_f32 v56, v56, v57
	v_cvt_pk_bf16_f32 v57, v66, v67
	v_mul_f32_e32 v66, v61, v61
	v_fmac_f32_e32 v66, v60, v60
	v_fmac_f32_e32 v66, v30, v30
	v_fmac_f32_e32 v66, v31, v31
	v_lshlrev_b32_e32 v30, 16, v58
	v_lshlrev_b32_e32 v60, 16, v62
	v_and_b32_e32 v31, 0xffff0000, v58
	v_and_b32_e32 v61, 0xffff0000, v62
	v_lshlrev_b32_e32 v58, 16, v59
	v_lshlrev_b32_e32 v62, 16, v63
	v_and_b32_e32 v59, 0xffff0000, v59
	v_and_b32_e32 v63, 0xffff0000, v63
	v_pk_add_f32 v[30:31], v[30:31], v[60:61]
	v_pk_add_f32 v[58:59], v[58:59], v[62:63]
	v_pk_fma_f32 v[24:25], s[6:7], v[24:25], v[30:31]
	v_pk_fma_f32 v[26:27], s[60:61], v[26:27], v[58:59]
	v_cvt_pk_bf16_f32 v30, v24, v25
	s_nop 0
	v_and_b32_e32 v59, 0xffff0000, v30
	v_sub_f32_e32 v59, v25, v59
	v_mul_f32_e32 v25, v25, v25
	v_cvt_pk_bf16_f32 v31, v26, v27
	v_lshlrev_b32_e32 v58, 16, v30
	v_lshlrev_b32_e32 v60, 16, v31
	v_and_b32_e32 v61, 0xffff0000, v31
	v_fmac_f32_e32 v25, v24, v24
	v_sub_f32_e32 v58, v24, v58
	v_sub_f32_e32 v60, v26, v60
	v_sub_f32_e32 v61, v27, v61
	v_fmac_f32_e32 v25, v26, v26
	v_cvt_pk_bf16_f32 v58, v58, v59
	v_cvt_pk_bf16_f32 v59, v60, v61
	v_fmac_f32_e32 v25, v27, v27
	v_lshl_add_u64 v[60:61], s[46:47], 0, v[80:81]
	v_add_f32_e32 v62, v66, v25
	global_store_dwordx4 v[60:61], v[28:31], off
	v_lshlrev_b32_e32 v24, 16, v48
	v_lshlrev_b32_e32 v26, 16, v52
	v_and_b32_e32 v25, 0xffff0000, v48
	v_and_b32_e32 v27, 0xffff0000, v52
	v_lshlrev_b32_e32 v30, 16, v49
	v_lshlrev_b32_e32 v48, 16, v53
	v_and_b32_e32 v31, 0xffff0000, v49
	v_and_b32_e32 v49, 0xffff0000, v53
	v_pk_add_f32 v[24:25], v[24:25], v[26:27]
	v_pk_add_f32 v[26:27], v[30:31], v[48:49]
	v_lshlrev_b32_e32 v48, 16, v55
	v_pk_fma_f32 v[22:23], s[60:61], v[22:23], v[26:27]
	v_pk_fma_f32 v[26:27], s[6:7], v[20:21], v[24:25]
	v_cvt_pk_bf16_f32 v21, v22, v23
	v_and_b32_e32 v49, 0xffff0000, v55
	v_cvt_pk_bf16_f32 v20, v26, v27
	v_lshlrev_b32_e32 v30, 16, v21
	v_and_b32_e32 v25, 0xffff0000, v20
	v_sub_f32_e32 v25, v27, v25
	v_mul_f32_e32 v27, v27, v27
	v_fmac_f32_e32 v27, v26, v26
	v_lshlrev_b32_e32 v24, 16, v20
	v_and_b32_e32 v31, 0xffff0000, v21
	v_fmac_f32_e32 v27, v22, v22
	v_sub_f32_e32 v24, v26, v24
	v_sub_f32_e32 v30, v22, v30
	v_sub_f32_e32 v31, v23, v31
	v_fmac_f32_e32 v27, v23, v23
	v_cvt_pk_bf16_f32 v24, v24, v25
	v_cvt_pk_bf16_f32 v25, v30, v31
	v_add_f32_e32 v52, v62, v27
	v_lshlrev_b32_e32 v22, 16, v50
	v_lshlrev_b32_e32 v26, 16, v54
	v_and_b32_e32 v23, 0xffff0000, v50
	v_and_b32_e32 v27, 0xffff0000, v54
	v_lshlrev_b32_e32 v30, 16, v51
	v_and_b32_e32 v31, 0xffff0000, v51
	v_pk_add_f32 v[22:23], v[22:23], v[26:27]
	v_pk_add_f32 v[26:27], v[30:31], v[48:49]
	v_pk_fma_f32 v[16:17], s[6:7], v[16:17], v[22:23]
	v_pk_fma_f32 v[18:19], s[60:61], v[18:19], v[26:27]
	v_cvt_pk_bf16_f32 v22, v16, v17
	v_lshl_add_u64 v[28:29], s[70:71], 0, v[80:81]
	v_and_b32_e32 v27, 0xffff0000, v22
	v_sub_f32_e32 v27, v17, v27
	v_mul_f32_e32 v17, v17, v17
	v_fmac_f32_e32 v17, v16, v16
	v_fmac_f32_e32 v17, v18, v18
	v_lshlrev_b32_e32 v26, 16, v22
	v_fmac_f32_e32 v17, v19, v19
	v_sub_f32_e32 v26, v16, v26
	v_add_f32_e32 v16, v52, v17
	v_mov_b32_e32 v17, v16
	s_nop 1
	v_permlane16_swap_b32_e32 v16, v17
	v_add_f32_e32 v16, v16, v17
	v_mov_b32_e32 v17, v16
	v_cvt_pk_bf16_f32 v23, v18, v19
	s_nop 1
	v_permlane32_swap_b32_e32 v16, v17
	v_lshlrev_b32_e32 v30, 16, v23
	v_and_b32_e32 v31, 0xffff0000, v23
	global_store_dwordx4 v[28:29], v[56:59], off
	v_sub_f32_e32 v30, v18, v30
	v_sub_f32_e32 v31, v19, v31
	v_cvt_pk_bf16_f32 v26, v26, v27
	v_cvt_pk_bf16_f32 v27, v30, v31
	global_store_dwordx4 v[60:61], v[20:23], off offset:64
	global_store_dwordx4 v[28:29], v[24:27], off offset:64
	s_and_saveexec_b64 s[36:37], s[0:1]
	s_cbranch_execz .LBB0_883
	v_add_f32_e32 v16, v16, v17
	global_atomic_add_f32 v[146:147], v16, off offset:640
; template <int EPI>
; __device__ __forceinline__ void gemm_epilogue(const f32x4 (&acc)[2][2][4][2], const Unit& u, int wr, int wc, int fr, int fq,
;                                               const EpiArgs& ea, const float (&rs_pre)[2][4]) {
;     ...
;     for (int it = 0; it < 8; ++it) {
;       const int ai = it >> 2, m = it & 3;
;       if (it + 1 < 8) EPI_LOAD_ROW(it + 1, hn, ln_, pq);
;       const int row = row0 + ai * 128 + m * 16;
;       float sq = 0.f;
; #pragma unroll
;       for (int bj = 0; bj < 2; ++bj) {
;         const size_t idx = (size_t)row * 1024 + lcp + bj * 32;
;         const uint32_t hw[4] = {hc[bj].x, hc[bj].y, hc[bj].z, hc[bj].w};
;         const uint32_t lw[4] = {lc[bj].x, lc[bj].y, lc[bj].z, lc[bj].w};
;         const uint32_t pw[4] = {pc[bj].x, pc[bj].y, pc[bj].z, pc[bj].w};
;         uint32_t ho[4], lo_[4];
; #pragma unroll
;         for (int n = 0; n < 2; ++n) {
;           f32x4 xv;
;           xv[0] = __uint_as_float(hw[2 * n] << 16) + __uint_as_float(lw[2 * n] << 16);
;           xv[1] = __uint_as_float(hw[2 * n] & 0xffff0000u) + __uint_as_float(lw[2 * n] & 0xffff0000u);
;           xv[2] = __uint_as_float(hw[2 * n + 1] << 16) + __uint_as_float(lw[2 * n + 1] << 16);
;           xv[3] = __uint_as_float(hw[2 * n + 1] & 0xffff0000u) + __uint_as_float(lw[2 * n + 1] & 0xffff0000u);
;           const f32x4 a = acc[ai][bj][m][n];
;           f32x4 v;
;           if constexpr (EPI == EPI_PLEGATE) {
;             const float rs = rsr[ai][m], rpe = rper[ai][m];
;             const float pv[4] = {__uint_as_float(pw[2 * n] << 16), __uint_as_float(pw[2 * n] & 0xffff0000u),
;                                  __uint_as_float(pw[2 * n + 1] << 16), __uint_as_float(pw[2 * n + 1] & 0xffff0000u)};
; #pragma unroll
;             for (int i = 0; i < 4; ++i) v[i] = xv[i] + sigmoidf_(a[i] * rs) * (pv[i] * rpe);
;           } else {
;             v = xv + a * ea.alpha;
;           }
;           const uint2 hnew = pack4(v);
;           ho[2 * n] = hnew.x; ho[2 * n + 1] = hnew.y;
;           if (ea.xf32_out) {
;             *reinterpret_cast<f32x4*>(ea.xf32_out + idx + 4 * n) = v;
;           } else {
;             f32x4 r;
;             r[0] = v[0] - __uint_as_float(hnew.x << 16);
;             r[1] = v[1] - __uint_as_float(hnew.x & 0xffff0000u);
;             r[2] = v[2] - __uint_as_float(hnew.y << 16);
.LBB0_883:
	s_waitcnt vmcnt(6)
	s_or_b64 exec, exec, s[36:37]
	v_lshlrev_b32_e32 v16, 16, v40
	v_lshlrev_b32_e32 v18, 16, v44
	v_and_b32_e32 v17, 0xffff0000, v40
	v_and_b32_e32 v19, 0xffff0000, v44
	v_lshlrev_b32_e32 v20, 16, v41
	v_lshlrev_b32_e32 v22, 16, v45
	v_and_b32_e32 v21, 0xffff0000, v41
	v_and_b32_e32 v23, 0xffff0000, v45
	v_pk_add_f32 v[16:17], v[16:17], v[18:19]
	v_pk_add_f32 v[18:19], v[20:21], v[22:23]
	v_lshlrev_b32_e32 v22, 16, v47
	v_pk_fma_f32 v[14:15], s[60:61], v[14:15], v[18:19]
	v_pk_fma_f32 v[18:19], s[6:7], v[12:13], v[16:17]
	v_cvt_pk_bf16_f32 v13, v14, v15
	v_and_b32_e32 v23, 0xffff0000, v47
	v_mul_f32_e32 v24, v19, v19
	v_cvt_pk_bf16_f32 v12, v18, v19
	v_lshlrev_b32_e32 v20, 16, v13
	v_lshlrev_b32_e32 v16, 16, v12
	v_and_b32_e32 v17, 0xffff0000, v12
	v_and_b32_e32 v21, 0xffff0000, v13
	v_fmac_f32_e32 v24, v18, v18
	v_sub_f32_e32 v16, v18, v16
	v_sub_f32_e32 v17, v19, v17
	v_sub_f32_e32 v20, v14, v20
	v_sub_f32_e32 v21, v15, v21
	v_fmac_f32_e32 v24, v14, v14
	v_cvt_pk_bf16_f32 v16, v16, v17
	v_cvt_pk_bf16_f32 v17, v20, v21
	v_fmac_f32_e32 v24, v15, v15
	v_lshlrev_b32_e32 v14, 16, v42
	v_lshlrev_b32_e32 v18, 16, v46
	v_and_b32_e32 v15, 0xffff0000, v42
	v_and_b32_e32 v19, 0xffff0000, v46
	v_lshlrev_b32_e32 v20, 16, v43
	v_and_b32_e32 v21, 0xffff0000, v43
	v_pk_add_f32 v[14:15], v[14:15], v[18:19]
	v_pk_add_f32 v[18:19], v[20:21], v[22:23]
	v_pk_fma_f32 v[8:9], s[6:7], v[8:9], v[14:15]
	v_pk_fma_f32 v[10:11], s[60:61], v[10:11], v[18:19]
	v_cvt_pk_bf16_f32 v14, v8, v9
	s_nop 0
	v_and_b32_e32 v19, 0xffff0000, v14
	v_cvt_pk_bf16_f32 v15, v10, v11
	v_lshlrev_b32_e32 v18, 16, v14
	v_sub_f32_e32 v19, v9, v19
	v_lshlrev_b32_e32 v20, 16, v15
	v_and_b32_e32 v21, 0xffff0000, v15
	v_mul_f32_e32 v9, v9, v9
	v_sub_f32_e32 v18, v8, v18
	v_sub_f32_e32 v20, v10, v20
	v_sub_f32_e32 v21, v11, v21
	v_fmac_f32_e32 v9, v8, v8
	v_cvt_pk_bf16_f32 v18, v18, v19
	v_cvt_pk_bf16_f32 v19, v20, v21
	v_fmac_f32_e32 v9, v10, v10
	v_lshl_add_u64 v[20:21], s[46:47], 0, v[64:65]
	v_fmac_f32_e32 v9, v11, v11
	global_store_dwordx4 v[20:21], v[12:15], off
	v_add_f32_e32 v22, v24, v9
	v_lshlrev_b32_e32 v8, 16, v32
	v_lshl_add_u64 v[12:13], s[70:71], 0, v[64:65]
	global_store_dwordx4 v[12:13], v[16:19], off
	v_lshlrev_b32_e32 v10, 16, v36
	v_and_b32_e32 v9, 0xffff0000, v32
	v_and_b32_e32 v11, 0xffff0000, v36
	v_lshlrev_b32_e32 v14, 16, v33
	v_lshlrev_b32_e32 v16, 16, v37
	v_and_b32_e32 v15, 0xffff0000, v33
	v_and_b32_e32 v17, 0xffff0000, v37
	v_pk_add_f32 v[8:9], v[8:9], v[10:11]
	v_pk_add_f32 v[10:11], v[14:15], v[16:17]
	v_lshlrev_b32_e32 v16, 16, v39
	v_pk_fma_f32 v[6:7], s[60:61], v[6:7], v[10:11]
	v_pk_fma_f32 v[10:11], s[6:7], v[4:5], v[8:9]
	v_cvt_pk_bf16_f32 v5, v6, v7
	v_and_b32_e32 v17, 0xffff0000, v39
	v_cvt_pk_bf16_f32 v4, v10, v11
	v_lshlrev_b32_e32 v14, 16, v5
	v_and_b32_e32 v9, 0xffff0000, v4
	v_sub_f32_e32 v9, v11, v9
	v_mul_f32_e32 v11, v11, v11
	v_fmac_f32_e32 v11, v10, v10
	v_lshlrev_b32_e32 v8, 16, v4
	v_and_b32_e32 v15, 0xffff0000, v5
	v_fmac_f32_e32 v11, v6, v6
	v_sub_f32_e32 v8, v10, v8
	v_sub_f32_e32 v14, v6, v14
	v_sub_f32_e32 v15, v7, v15
	v_fmac_f32_e32 v11, v7, v7
	v_cvt_pk_bf16_f32 v8, v8, v9
	v_cvt_pk_bf16_f32 v9, v14, v15
	v_add_f32_e32 v18, v22, v11
	v_lshlrev_b32_e32 v6, 16, v34
	v_lshlrev_b32_e32 v10, 16, v38
	v_and_b32_e32 v7, 0xffff0000, v34
	v_and_b32_e32 v11, 0xffff0000, v38
	v_lshlrev_b32_e32 v14, 16, v35
	v_and_b32_e32 v15, 0xffff0000, v35
	v_pk_add_f32 v[6:7], v[6:7], v[10:11]
	v_pk_add_f32 v[10:11], v[14:15], v[16:17]
	v_pk_fma_f32 v[0:1], s[6:7], v[0:1], v[6:7]
	v_pk_fma_f32 v[2:3], s[60:61], v[2:3], v[10:11]
	v_cvt_pk_bf16_f32 v6, v0, v1
	s_nop 0
	v_and_b32_e32 v11, 0xffff0000, v6
	v_sub_f32_e32 v11, v1, v11
	v_mul_f32_e32 v1, v1, v1
	v_fmac_f32_e32 v1, v0, v0
	v_fmac_f32_e32 v1, v2, v2
	v_lshlrev_b32_e32 v10, 16, v6
	v_fmac_f32_e32 v1, v3, v3
	v_sub_f32_e32 v10, v0, v10
	v_add_f32_e32 v0, v18, v1
	v_mov_b32_e32 v1, v0
	s_nop 1
	v_permlane16_swap_b32_e32 v0, v1
	v_add_f32_e32 v0, v0, v1
	v_mov_b32_e32 v1, v0
	v_cvt_pk_bf16_f32 v7, v2, v3
	s_nop 1
	v_permlane32_swap_b32_e32 v0, v1
	v_lshlrev_b32_e32 v14, 16, v7
	v_and_b32_e32 v15, 0xffff0000, v7
	v_sub_f32_e32 v14, v2, v14
	v_sub_f32_e32 v15, v3, v15
	v_cvt_pk_bf16_f32 v10, v10, v11
	v_cvt_pk_bf16_f32 v11, v14, v15
	global_store_dwordx4 v[20:21], v[4:7], off offset:64
	global_store_dwordx4 v[12:13], v[8:11], off offset:64
	s_and_saveexec_b64 s[36:37], s[0:1]
	s_cbranch_execz .LBB0_855
	v_add_f32_e32 v0, v0, v1
	global_atomic_add_f32 v[146:147], v0, off offset:704
	s_branch .LBB0_855
